# attention KV loop: per-wave counted DMA wait (waves issuing three pieces per step wait vmcnt(6), the two-piece waves vmcnt(4))
# speedup vs baseline: 1.0009x; 1.0009x over previous
.LBB0_746:
	s_cmp_lt_i32 s43, 6
	s_cbranch_scc0 .Lattn_w4
	s_waitcnt vmcnt(6)
	s_branch .LBB0_747
